# DRAM-page locality: conversion routine gives each wave three adjacent items (384 B contiguous per source row) instead of items NGW apart
# baseline (speedup 1.0000x reference)
;     ...
;     for (int mi = 0; mi < 7 * DEPTH; ++mi) {
;         if (!((mask >> mi) & 1u)) continue;
;         const int l = mi / 7, kind = mi - 7 * l;
;         const float* W; const float* ks = nullptr; bf16_t* WT; int K, N, rm = 0;
;         if (kind == 0)      { W = a.in[2] + (size_t)l * 2048 * 7680;  K = 2048; N = 7680; WT = (bf16_t*)(ws + WS_WIN + l * SZ_WIN); ks = a.in[1] + l * 2048; rm = 3; }
;         else if (kind == 1) { W = a.in[10] + (size_t)l * 1024 * 2048; K = 1024; N = 2048; WT = (bf16_t*)(ws + WS_WA + l * SZ_WA); }
;         else if (kind == 2) { W = a.in[11] + (size_t)l * 1024 * 2048; K = 1024; N = 2048; WT = (bf16_t*)(ws + WS_WB + l * SZ_WB); }
;         else if (kind == 3) { W = a.in[12] + (size_t)l * 2048 * 2048; K = 2048; N = 2048; WT = (bf16_t*)(ws + WS_WO + l * SZ_WO); }
;         else if (kind == 4) { W = a.in[14] + (size_t)l * 2048 * 5632; K = 2048; N = 5632; WT = (bf16_t*)(ws + WS_WGU + l * SZ_WGU); ks = a.in[13] + l * 2048; rm = 1; }
;         else if (kind == 5) { W = a.in[15] + (size_t)l * 2048 * 5632; K = 2048; N = 5632; WT = (bf16_t*)(ws + WS_WGU + l * SZ_WGU); ks = a.in[13] + l * 2048; rm = 2; }
;         else                { W = a.in[16] + (size_t)l * 5632 * 2048; K = 5632; N = 2048; WT = (bf16_t*)(ws + WS_WD + l * SZ_WD); }
;         const int nitems = (K >> 6) * (N >> 5);
;         int ilo = 0, ihi = nitems; if ((fmask >> mi) & 1u) { ilo = (nitems * flo) >> 4; ihi = (nitems * fhi) >> 4; }
;         const int cnt = ihi - ilo;
;         int first = (gw - base) % NGW; if (first < 0) first += NGW;
;         for (int it = first; it < cnt; it += NGW) tr_item(W, K, N, WT, ks, rm, ilo + it, lane);
;         base = (base + cnt) % NGW;
.Lsl_p0_set0:
	v_readlane_b32 s22, v250, 6
	v_readlane_b32 s23, v250, 7
	v_readlane_b32 s24, v250, 36
	v_readlane_b32 s25, v250, 37
	v_readlane_b32 s44, v250, 4
	v_readlane_b32 s45, v250, 5
	v_mul_u32_u24_e32 v104, 0x3c000, v102
	v_lshl_add_u32 v104, v103, 4, v104
	v_mul_u32_u24_e32 v105, 0x4000, v103
	v_lshl_add_u32 v105, v102, 4, v105
	s_add_u32 s24, s24, 0x1c0000
	s_addc_u32 s25, s25, 0
	s_mov_b32 s48, 0x7800
	s_mov_b32 s49, 0x1e0000
	s_movk_i32 s50, 8739
	s_mov_b32 s51, 21
	s_movk_i32 s52, 240
	s_movk_i32 s53, 0x1000
	s_mov_b32 s54, 3
	s_mov_b32 s55, 1
	s_movk_i32 s56, 0
	s_movk_i32 s47, 7680
	s_sub_i32 s4, s12, 0
	s_and_b32 s4, s4, 2047
	s_mul_i32 s4, s4, 3
	s_branch .Lsl_p0_loop
.Lsl_p0_set1:
	v_readlane_b32 s22, v250, 22
	v_readlane_b32 s23, v250, 23
	v_readlane_b32 s24, v250, 36
	v_readlane_b32 s25, v250, 37
	v_mul_u32_u24_e32 v104, 0x10000, v102
	v_lshl_add_u32 v104, v103, 4, v104
	v_mul_u32_u24_e32 v105, 0x2000, v103
	v_lshl_add_u32 v105, v102, 4, v105
	s_add_u32 s24, s24, 0x3dc0000
	s_addc_u32 s25, s25, 0
	s_mov_b32 s48, 0x2000
	s_mov_b32 s49, 0x80000
	s_movk_i32 s50, 1
	s_mov_b32 s51, 6
	s_movk_i32 s52, 64
	s_movk_i32 s53, 0x800
	s_mov_b32 s54, 0
	s_mov_b32 s55, 0
	s_movk_i32 s56, 0
	s_movk_i32 s47, 1024
	s_sub_i32 s4, s12, 512
	s_and_b32 s4, s4, 2047
	s_mul_i32 s4, s4, 3
	s_branch .Lsl_p0_loop
.Lsl_p0_set2:
	v_readlane_b32 s22, v250, 24
	v_readlane_b32 s23, v250, 25
	v_readlane_b32 s24, v250, 36
	v_readlane_b32 s25, v250, 37
	v_mul_u32_u24_e32 v104, 0x10000, v102
	v_lshl_add_u32 v104, v103, 4, v104
	v_mul_u32_u24_e32 v105, 0x2000, v103
	v_lshl_add_u32 v105, v102, 4, v105
	s_add_u32 s24, s24, 0x45c0000
	s_addc_u32 s25, s25, 0
	s_mov_b32 s48, 0x2000
	s_mov_b32 s49, 0x80000
	s_movk_i32 s50, 1
	s_mov_b32 s51, 6
	s_movk_i32 s52, 64
	s_movk_i32 s53, 0x800
	s_mov_b32 s54, 0
	s_mov_b32 s55, 0
	s_movk_i32 s56, 0
	s_movk_i32 s47, 1024
	s_sub_i32 s4, s12, 854
	s_and_b32 s4, s4, 2047
	s_mul_i32 s4, s4, 3
	s_branch .Lsl_p0_loop
.Lsl_p0_set3:
	v_readlane_b32 s22, v250, 26
	v_readlane_b32 s23, v250, 27
	v_readlane_b32 s24, v250, 36
	v_readlane_b32 s25, v250, 37
	v_mul_u32_u24_e32 v104, 0x10000, v102
	v_lshl_add_u32 v104, v103, 4, v104
	v_mul_u32_u24_e32 v105, 0x4000, v103
	v_lshl_add_u32 v105, v102, 4, v105
	s_add_u32 s24, s24, 0x4dc0000
	s_addc_u32 s25, s25, 0
	s_mov_b32 s48, 0x2000
	s_mov_b32 s49, 0x80000
	s_movk_i32 s50, 1
	s_mov_b32 s51, 6
	s_movk_i32 s52, 64
	s_movk_i32 s53, 0x1000
	s_mov_b32 s54, 0
	s_mov_b32 s55, 0
	s_movk_i32 s56, 0
	s_movk_i32 s47, 2048
	s_sub_i32 s4, s12, 1196
	s_and_b32 s4, s4, 2047
	s_mul_i32 s4, s4, 3
	s_branch .Lsl_p0_loop

; __device__ __forceinline__ void tr_item(const float* __restrict__ W, int K, int N, bf16_t* WT, const float* __restrict__ kscale, int rowmode, int item, int lane) {
;     const int nblk = N >> 5, kb = item / nblk, nb = item - kb * nblk;
;     const int c = lane >> 3, q = lane & 7, k0 = kb * 64 + c * 8, n0 = nb * 32 + q * 4;
;     ...
;         const int nitems = (K >> 6) * (N >> 5);
;         int ilo = 0, ihi = nitems; if ((fmask >> mi) & 1u) { ilo = (nitems * flo) >> 4; ihi = (nitems * fhi) >> 4; }
;         const int cnt = ihi - ilo;
;         int first = (gw - base) % NGW; if (first < 0) first += NGW;
;         for (int it = first; it < cnt; it += NGW) tr_item(W, K, N, WT, ks, rm, ilo + it, lane);
;         base = (base + cnt) % NGW;
.Lsl_p0_rmd2:
	s_mul_i32 s19, s19, s53
	s_lshl_b32 s20, s17, 7
	s_add_i32 s19, s19, s20
	v_add_u32_e32 v44, s19, v105
	s_add_i32 s4, s4, 1
	s_cmp_ge_u32 s4, s47
	s_cbranch_scc1 .Lsl_p0_single
	s_add_i32 s16, s4, s56
	s_mul_i32 s17, s16, s50
	s_lshr_b32 s17, s17, s51
	s_mul_i32 s19, s17, s52
	s_sub_i32 s18, s16, s19
	s_mul_i32 s19, s17, s49
	s_lshl_b32 s20, s18, 7
	s_add_i32 s19, s19, s20
	v_add_u32_e32 v42, s19, v104
	s_cmp_eq_u32 s55, 0
	s_cbranch_scc1 .Lsl_p0_nks4
	s_lshl_b32 s19, s17, 8
	v_add_u32_e32 v43, s19, v110
	global_load_dwordx4 v[78:81], v43, s[44:45]
	global_load_dwordx4 v[82:85], v43, s[44:45] offset:16

; __device__ __forceinline__ void tr_item(const float* __restrict__ W, int K, int N, bf16_t* WT, const float* __restrict__ kscale, int rowmode, int item, int lane) {
;     const int nblk = N >> 5, kb = item / nblk, nb = item - kb * nblk;
;     const int c = lane >> 3, q = lane & 7, k0 = kb * 64 + c * 8, n0 = nb * 32 + q * 4;
;     ...
;         const int nitems = (K >> 6) * (N >> 5);
;         int ilo = 0, ihi = nitems; if ((fmask >> mi) & 1u) { ilo = (nitems * flo) >> 4; ihi = (nitems * fhi) >> 4; }
;         const int cnt = ihi - ilo;
;         int first = (gw - base) % NGW; if (first < 0) first += NGW;
;         for (int it = first; it < cnt; it += NGW) tr_item(W, K, N, WT, ks, rm, ilo + it, lane);
;         base = (base + cnt) % NGW;
.Lsl_p0_rmd5:
	s_mul_i32 s19, s19, s53
	s_lshl_b32 s20, s17, 7
	s_add_i32 s19, s19, s20
	v_add_u32_e32 v45, s19, v105
	s_add_i32 s4, s4, 1
	s_cmp_ge_u32 s4, s47
	s_cbranch_scc1 .Lsl_p0_pair
	s_add_i32 s16, s4, s56
	s_mul_i32 s17, s16, s50
	s_lshr_b32 s17, s17, s51
	s_mul_i32 s19, s17, s52
	s_sub_i32 s18, s16, s19
	s_mul_i32 s19, s17, s49
	s_lshl_b32 s20, s18, 7
	s_add_i32 s19, s19, s20
	v_add_u32_e32 v42, s19, v104
	s_cmp_eq_u32 s55, 0
	s_cbranch_scc1 .Lsl_p0_nks7
	s_lshl_b32 s19, s17, 8
	v_add_u32_e32 v43, s19, v110
	global_load_dwordx4 v[144:147], v43, s[44:45]
	global_load_dwordx4 v[148:151], v43, s[44:45] offset:16

;     ...
;         const int nitems = (K >> 6) * (N >> 5);
;         int ilo = 0, ihi = nitems; if ((fmask >> mi) & 1u) { ilo = (nitems * flo) >> 4; ihi = (nitems * fhi) >> 4; }
;         const int cnt = ihi - ilo;
;         int first = (gw - base) % NGW; if (first < 0) first += NGW;
;         for (int it = first; it < cnt; it += NGW) tr_item(W, K, N, WT, ks, rm, ilo + it, lane);
;         base = (base + cnt) % NGW;
.Lsl_p0_rmd8:
	s_mul_i32 s19, s19, s53
	s_lshl_b32 s20, s17, 7
	s_add_i32 s19, s19, s20
	v_add_u32_e32 v111, s19, v105
	s_add_i32 s4, s4, 6142
	s_cmp_eq_u32 s55, 0
	s_cbranch_scc1 .Lsl_p0_w810
	s_waitcnt vmcnt(20)
	s_branch .Lsl_p0_wd11

;     ...
;         const int nitems = (K >> 6) * (N >> 5);
;         int ilo = 0, ihi = nitems; if ((fmask >> mi) & 1u) { ilo = (nitems * flo) >> 4; ihi = (nitems * fhi) >> 4; }
;         const int cnt = ihi - ilo;
;         int first = (gw - base) % NGW; if (first < 0) first += NGW;
;         for (int it = first; it < cnt; it += NGW) tr_item(W, K, N, WT, ks, rm, ilo + it, lane);
;         base = (base + cnt) % NGW;
; __global__ void __launch_bounds__(NTHREADS, 2) mk_fwd(Args args) {
;     ...
;             { int thr = S.nwg - ((S.nwg + G - 1) / G - 1) * G; if (thr >= G) thr = 0;
;                 if (blk >= thr) p0_prologue(args, (blk - thr) * NWAVES + wave, (G - thr) * NWAVES, lane, l == 0 ? 0x0030u : 0x1800u, false, l == 0 ? 0x0010u : 0x0800u, 10, 16); }
.Lsl_in_set0:
	v_readlane_b32 s22, v250, 30
	v_readlane_b32 s23, v250, 31
	v_readlane_b32 s24, v250, 36
	v_readlane_b32 s25, v250, 37
	v_readlane_b32 s26, v250, 28
	v_readlane_b32 s27, v250, 29
	v_mul_u32_u24_e32 v104, 0x2c000, v102
	v_lshl_add_u32 v104, v103, 4, v104
	v_mul_u32_u24_e32 v105, 0x4000, v103
	v_lshl_add_u32 v105, v102, 4, v105
	s_add_u32 s24, s24, 0x5dc0000
	s_addc_u32 s25, s25, 0
	s_mov_b32 s36, 0x5800
	s_mov_b32 s37, 0x160000
	s_movk_i32 s38, 2979
	s_mov_b32 s39, 19
	s_movk_i32 s40, 176
	s_movk_i32 s41, 0x1000
	s_mov_b32 s42, 1
	s_mov_b32 s43, 1
	s_movk_i32 s44, 3520
	s_movk_i32 s29, 2112
	s_sub_i32 s4, s2, 0
	s_and_b32 s4, s4, 511
	s_mul_i32 s4, s4, 3
	s_branch .Lsl_in_loop
.Lsl_in_set1:
	v_readlane_b32 s22, v250, 32
	v_readlane_b32 s23, v250, 33
	v_readlane_b32 s24, v250, 36
	v_readlane_b32 s25, v250, 37
	v_readlane_b32 s26, v250, 28
	v_readlane_b32 s27, v250, 29
	v_mul_u32_u24_e32 v104, 0x2c000, v102
	v_lshl_add_u32 v104, v103, 4, v104
	v_mul_u32_u24_e32 v105, 0x4000, v103
	v_lshl_add_u32 v105, v102, 4, v105
	s_add_u32 s24, s24, 0x5dc0000
	s_addc_u32 s25, s25, 0
	s_mov_b32 s36, 0x5800
	s_mov_b32 s37, 0x160000
	s_movk_i32 s38, 2979
	s_mov_b32 s39, 19
	s_movk_i32 s40, 176
	s_movk_i32 s41, 0x1000
	s_mov_b32 s42, 2
	s_mov_b32 s43, 1
	s_movk_i32 s44, 0
	s_movk_i32 s29, 5632
	s_sub_i32 s4, s2, 192
	s_and_b32 s4, s4, 511
	s_mul_i32 s4, s4, 3
	s_branch .Lsl_in_loop
.Lsl_in_set16:
	v_readlane_b32 s22, v250, 30
	v_readlane_b32 s23, v250, 31
	v_readlane_b32 s24, v250, 36
	v_readlane_b32 s25, v250, 37
	v_readlane_b32 s26, v250, 28
	v_readlane_b32 s27, v250, 29
	v_mul_u32_u24_e32 v104, 0x2c000, v102
	v_lshl_add_u32 v104, v103, 4, v104
	v_mul_u32_u24_e32 v105, 0x4000, v103
	v_lshl_add_u32 v105, v102, 4, v105
	s_add_u32 s22, s22, 0x2c00000
	s_addc_u32 s23, s23, 0
	s_add_u32 s24, s24, 0x89c0000
	s_addc_u32 s25, s25, 0
	s_add_u32 s26, s26, 0x2000
	s_addc_u32 s27, s27, 0
	s_mov_b32 s36, 0x5800
	s_mov_b32 s37, 0x160000
	s_movk_i32 s38, 2979
	s_mov_b32 s39, 19
	s_movk_i32 s40, 176
	s_movk_i32 s41, 0x1000
	s_mov_b32 s42, 1
	s_mov_b32 s43, 1
	s_movk_i32 s44, 3520
	s_movk_i32 s29, 2112
	s_sub_i32 s4, s2, 0
	s_and_b32 s4, s4, 511
	s_mul_i32 s4, s4, 3
	s_branch .Lsl_in_loop
.Lsl_in_set17:
	v_readlane_b32 s22, v250, 32
	v_readlane_b32 s23, v250, 33
	v_readlane_b32 s24, v250, 36
	v_readlane_b32 s25, v250, 37
	v_readlane_b32 s26, v250, 28
	v_readlane_b32 s27, v250, 29
	v_mul_u32_u24_e32 v104, 0x2c000, v102
	v_lshl_add_u32 v104, v103, 4, v104
	v_mul_u32_u24_e32 v105, 0x4000, v103
	v_lshl_add_u32 v105, v102, 4, v105
	s_add_u32 s22, s22, 0x2c00000
	s_addc_u32 s23, s23, 0
	s_add_u32 s24, s24, 0x89c0000
	s_addc_u32 s25, s25, 0
	s_add_u32 s26, s26, 0x2000
	s_addc_u32 s27, s27, 0
	s_mov_b32 s36, 0x5800
	s_mov_b32 s37, 0x160000
	s_movk_i32 s38, 2979
	s_mov_b32 s39, 19
	s_movk_i32 s40, 176
	s_movk_i32 s41, 0x1000
	s_mov_b32 s42, 2
	s_mov_b32 s43, 1
	s_movk_i32 s44, 0
	s_movk_i32 s29, 5632
	s_sub_i32 s4, s2, 192
	s_and_b32 s4, s4, 511
	s_mul_i32 s4, s4, 3
	s_branch .Lsl_in_loop

;     ...
;         const int nitems = (K >> 6) * (N >> 5);
;         int ilo = 0, ihi = nitems; if ((fmask >> mi) & 1u) { ilo = (nitems * flo) >> 4; ihi = (nitems * fhi) >> 4; }
;         const int cnt = ihi - ilo;
;         int first = (gw - base) % NGW; if (first < 0) first += NGW;
;         for (int it = first; it < cnt; it += NGW) tr_item(W, K, N, WT, ks, rm, ilo + it, lane);
;         base = (base + cnt) % NGW;
.Lsl_in_rmd2:
	s_mul_i32 s19, s19, s41
	s_lshl_b32 s20, s17, 7
	s_add_i32 s19, s19, s20
	v_add_u32_e32 v44, s19, v105
	s_add_i32 s4, s4, 1
	s_cmp_ge_u32 s4, s29
	s_cbranch_scc1 .Lsl_in_single
	s_add_i32 s16, s4, s44
	s_mul_i32 s17, s16, s38
	s_lshr_b32 s17, s17, s39
	s_mul_i32 s19, s17, s40
	s_sub_i32 s18, s16, s19
	s_mul_i32 s19, s17, s37
	s_lshl_b32 s20, s18, 7
	s_add_i32 s19, s19, s20
	v_add_u32_e32 v42, s19, v104
	s_cmp_eq_u32 s43, 0
	s_cbranch_scc1 .Lsl_in_nks4
	s_lshl_b32 s19, s17, 8
	v_add_u32_e32 v43, s19, v110
	global_load_dwordx4 v[78:81], v43, s[26:27]
	global_load_dwordx4 v[82:85], v43, s[26:27] offset:16

;     ...
;         const int nitems = (K >> 6) * (N >> 5);
;         int ilo = 0, ihi = nitems; if ((fmask >> mi) & 1u) { ilo = (nitems * flo) >> 4; ihi = (nitems * fhi) >> 4; }
;         const int cnt = ihi - ilo;
;         int first = (gw - base) % NGW; if (first < 0) first += NGW;
;         for (int it = first; it < cnt; it += NGW) tr_item(W, K, N, WT, ks, rm, ilo + it, lane);
;         base = (base + cnt) % NGW;
.Lsl_in_rmd5:
	s_mul_i32 s19, s19, s41
	s_lshl_b32 s20, s17, 7
	s_add_i32 s19, s19, s20
	v_add_u32_e32 v45, s19, v105
	s_add_i32 s4, s4, 1
	s_cmp_ge_u32 s4, s29
	s_cbranch_scc1 .Lsl_in_pair
	s_add_i32 s16, s4, s44
	s_mul_i32 s17, s16, s38
	s_lshr_b32 s17, s17, s39
	s_mul_i32 s19, s17, s40
	s_sub_i32 s18, s16, s19
	s_mul_i32 s19, s17, s37
	s_lshl_b32 s20, s18, 7
	s_add_i32 s19, s19, s20
	v_add_u32_e32 v42, s19, v104
	s_cmp_eq_u32 s43, 0
	s_cbranch_scc1 .Lsl_in_nks7
	s_lshl_b32 s19, s17, 8
	v_add_u32_e32 v43, s19, v110
	global_load_dwordx4 v[144:147], v43, s[26:27]
	global_load_dwordx4 v[148:151], v43, s[26:27] offset:16

;     ...
;         const int nitems = (K >> 6) * (N >> 5);
;         int ilo = 0, ihi = nitems; if ((fmask >> mi) & 1u) { ilo = (nitems * flo) >> 4; ihi = (nitems * fhi) >> 4; }
;         const int cnt = ihi - ilo;
;         int first = (gw - base) % NGW; if (first < 0) first += NGW;
;         for (int it = first; it < cnt; it += NGW) tr_item(W, K, N, WT, ks, rm, ilo + it, lane);
;         base = (base + cnt) % NGW;
.Lsl_in_rmd8:
	s_mul_i32 s19, s19, s41
	s_lshl_b32 s20, s17, 7
	s_add_i32 s19, s19, s20
	v_add_u32_e32 v111, s19, v105
	s_add_i32 s4, s4, 1534
	s_cmp_eq_u32 s43, 0
	s_cbranch_scc1 .Lsl_in_w810
	s_waitcnt vmcnt(20)
	s_branch .Lsl_in_wd11

;     ...
;         const int nitems = (K >> 6) * (N >> 5);
;         int ilo = 0, ihi = nitems; if ((fmask >> mi) & 1u) { ilo = (nitems * flo) >> 4; ihi = (nitems * fhi) >> 4; }
;         const int cnt = ihi - ilo;
;         int first = (gw - base) % NGW; if (first < 0) first += NGW;
;         for (int it = first; it < cnt; it += NGW) tr_item(W, K, N, WT, ks, rm, ilo + it, lane);
;         base = (base + cnt) % NGW;
; __global__ void __launch_bounds__(NTHREADS, 2) mk_fwd(Args args) {
;     ...
;             { int thr = S.nwg - ((S.nwg + G - 1) / G - 1) * G; if (thr >= G) thr = 0;
;                 if (blk >= thr) p0_prologue(args, (blk - thr) * NWAVES + wave, (G - thr) * NWAVES, lane, l == 0 ? 0x07C0u : 0x2000u, false); }
.Lsl_gu_set0:
	s_mov_b64 s[22:23], s[88:89]
	v_readlane_b32 s24, v250, 36
	v_readlane_b32 s25, v250, 37
	v_mul_u32_u24_e32 v104, 0x10000, v102
	v_lshl_add_u32 v104, v103, 4, v104
	v_mul_u32_u24_e32 v105, 0xb000, v103
	v_lshl_add_u32 v105, v102, 4, v105
	s_add_u32 s24, s24, 0xb5c0000
	s_addc_u32 s25, s25, 0
	s_mov_b32 s36, 0x2000
	s_mov_b32 s37, 0x80000
	s_movk_i32 s38, 1
	s_mov_b32 s39, 6
	s_movk_i32 s40, 64
	s_movk_i32 s41, 0x2c00
	s_mov_b32 s42, 0
	s_mov_b32 s43, 0
	s_movk_i32 s44, 0
	s_movk_i32 s29, 5632
	s_sub_i32 s4, s2, 0
	s_and_b32 s4, s4, 1023
	s_mul_i32 s4, s4, 3
	s_branch .Lsl_gu_loop
.Lsl_gu_set1:
	v_readlane_b32 s22, v250, 6
	v_readlane_b32 s23, v250, 7
	v_readlane_b32 s24, v250, 36
	v_readlane_b32 s25, v250, 37
	v_readlane_b32 s26, v250, 4
	v_readlane_b32 s27, v250, 5
	v_mul_u32_u24_e32 v104, 0x3c000, v102
	v_lshl_add_u32 v104, v103, 4, v104
	v_mul_u32_u24_e32 v105, 0x4000, v103
	v_lshl_add_u32 v105, v102, 4, v105
	s_add_u32 s22, s22, 0x3c00000
	s_addc_u32 s23, s23, 0
	s_add_u32 s24, s24, 0x1fc0000
	s_addc_u32 s25, s25, 0
	s_add_u32 s26, s26, 0x2000
	s_addc_u32 s27, s27, 0
	s_mov_b32 s36, 0x7800
	s_mov_b32 s37, 0x1e0000
	s_movk_i32 s38, 8739
	s_mov_b32 s39, 21
	s_movk_i32 s40, 240
	s_movk_i32 s41, 0x1000
	s_mov_b32 s42, 3
	s_mov_b32 s43, 1
	s_movk_i32 s44, 0
	s_movk_i32 s29, 7680
	s_sub_i32 s4, s2, 854
	s_and_b32 s4, s4, 1023
	s_mul_i32 s4, s4, 3
	s_branch .Lsl_gu_loop
.Lsl_gu_set2:
	v_readlane_b32 s22, v250, 22
	v_readlane_b32 s23, v250, 23
	v_readlane_b32 s24, v250, 36
	v_readlane_b32 s25, v250, 37
	v_mul_u32_u24_e32 v104, 0x10000, v102
	v_lshl_add_u32 v104, v103, 4, v104
	v_mul_u32_u24_e32 v105, 0x2000, v103
	v_lshl_add_u32 v105, v102, 4, v105
	s_add_u32 s22, s22, 0x800000
	s_addc_u32 s23, s23, 0
	s_add_u32 s24, s24, 0x41c0000
	s_addc_u32 s25, s25, 0
	s_mov_b32 s36, 0x2000
	s_mov_b32 s37, 0x80000
	s_movk_i32 s38, 1
	s_mov_b32 s39, 6
	s_movk_i32 s40, 64
	s_movk_i32 s41, 0x800
	s_mov_b32 s42, 0
	s_mov_b32 s43, 0
	s_movk_i32 s44, 0
	s_movk_i32 s29, 1024
	s_sub_i32 s4, s2, 342
	s_and_b32 s4, s4, 1023
	s_mul_i32 s4, s4, 3
	s_branch .Lsl_gu_loop
.Lsl_gu_set3:
	v_readlane_b32 s22, v250, 24
	v_readlane_b32 s23, v250, 25
	v_readlane_b32 s24, v250, 36
	v_readlane_b32 s25, v250, 37
	v_mul_u32_u24_e32 v104, 0x10000, v102
	v_lshl_add_u32 v104, v103, 4, v104
	v_mul_u32_u24_e32 v105, 0x2000, v103
	v_lshl_add_u32 v105, v102, 4, v105
	s_add_u32 s22, s22, 0x800000
	s_addc_u32 s23, s23, 0
	s_add_u32 s24, s24, 0x49c0000
	s_addc_u32 s25, s25, 0
	s_mov_b32 s36, 0x2000
	s_mov_b32 s37, 0x80000
	s_movk_i32 s38, 1
	s_mov_b32 s39, 6
	s_movk_i32 s40, 64
	s_movk_i32 s41, 0x800
	s_mov_b32 s42, 0
	s_mov_b32 s43, 0
	s_movk_i32 s44, 0
	s_movk_i32 s29, 1024
	s_sub_i32 s4, s2, 684
	s_and_b32 s4, s4, 1023
	s_mul_i32 s4, s4, 3
	s_branch .Lsl_gu_loop
.Lsl_gu_set4:
	v_readlane_b32 s22, v250, 26
	v_readlane_b32 s23, v250, 27
	v_readlane_b32 s24, v250, 36
	v_readlane_b32 s25, v250, 37
	v_mul_u32_u24_e32 v104, 0x10000, v102
	v_lshl_add_u32 v104, v103, 4, v104
	v_mul_u32_u24_e32 v105, 0x4000, v103
	v_lshl_add_u32 v105, v102, 4, v105
	s_add_u32 s22, s22, 0x1000000
	s_addc_u32 s23, s23, 0
	s_add_u32 s24, s24, 0x55c0000
	s_addc_u32 s25, s25, 0
	s_mov_b32 s36, 0x2000
	s_mov_b32 s37, 0x80000
	s_movk_i32 s38, 1
	s_mov_b32 s39, 6
	s_movk_i32 s40, 64
	s_movk_i32 s41, 0x1000
	s_mov_b32 s42, 0
	s_mov_b32 s43, 0
	s_movk_i32 s44, 0
	s_movk_i32 s29, 2048
	s_sub_i32 s4, s2, 2
	s_and_b32 s4, s4, 1023
	s_mul_i32 s4, s4, 3
	s_branch .Lsl_gu_loop
.Lsl_gu_set16:
	s_mov_b64 s[22:23], s[88:89]
	v_readlane_b32 s24, v250, 36
	v_readlane_b32 s25, v250, 37
	v_mul_u32_u24_e32 v104, 0x10000, v102
	v_lshl_add_u32 v104, v103, 4, v104
	v_mul_u32_u24_e32 v105, 0xb000, v103
	v_lshl_add_u32 v105, v102, 4, v105
	s_add_u32 s22, s22, 0x2c00000
	s_addc_u32 s23, s23, 0
	s_add_u32 s24, s24, 0xcbc0000
	s_addc_u32 s25, s25, 0
	s_mov_b32 s36, 0x2000
	s_mov_b32 s37, 0x80000
	s_movk_i32 s38, 1
	s_mov_b32 s39, 6
	s_movk_i32 s40, 64
	s_movk_i32 s41, 0x2c00
	s_mov_b32 s42, 0
	s_mov_b32 s43, 0
	s_movk_i32 s44, 0
	s_movk_i32 s29, 5632
	s_sub_i32 s4, s2, 0
	s_and_b32 s4, s4, 1023
	s_mul_i32 s4, s4, 3
	s_branch .Lsl_gu_loop

;     ...
;         const int nitems = (K >> 6) * (N >> 5);
;         int ilo = 0, ihi = nitems; if ((fmask >> mi) & 1u) { ilo = (nitems * flo) >> 4; ihi = (nitems * fhi) >> 4; }
;         const int cnt = ihi - ilo;
;         int first = (gw - base) % NGW; if (first < 0) first += NGW;
;         for (int it = first; it < cnt; it += NGW) tr_item(W, K, N, WT, ks, rm, ilo + it, lane);
;         base = (base + cnt) % NGW;
.Lsl_gu_rmd8:
	s_mul_i32 s19, s19, s41
	s_lshl_b32 s20, s17, 7
	s_add_i32 s19, s19, s20
	v_add_u32_e32 v111, s19, v105
	s_add_i32 s4, s4, 3070
	s_cmp_eq_u32 s43, 0
	s_cbranch_scc1 .Lsl_gu_w810
	s_waitcnt vmcnt(20)
	s_branch .Lsl_gu_wd11
